# loop-edge edit: back edge of both attention loops rotated (loop-counter SALU and exit test moved in front of the per-iteration barrier, exit path gets its own barrier copy), on top of v10
# speedup vs baseline: 1.0038x; 1.0027x over previous
.LBB0_445:
	s_add_i32 s12, s18, 1
	s_cmp_lg_u32 s18, 2
	s_cselect_b32 s13, s12, 0
	s_add_i32 s15, s15, 1
	s_add_i32 s8, s8, 2
	s_add_i32 s76, s76, 64
	s_cmp_eq_u32 s9, s15
	s_cbranch_scc1 .Lmy_exit_mla
	s_mov_b32 s12, s18
	s_mov_b32 s24, s19
	s_mov_b32 s18, s13
	s_mov_b32 s19, s12
	s_add_i32 s12, s15, 0x42
	s_cmp_ge_i32 s12, s7
	s_waitcnt lgkmcnt(0)
	s_barrier
	s_cbranch_scc0 .LBB0_428
	s_branch .LBB0_429
.Lmy_exit_mla:
	s_waitcnt lgkmcnt(0)
	s_barrier
	s_branch .LBB0_447

.LBB0_702:
	v_mov_b32_e32 v216, v1
	v_mov_b32_e32 v217, v6
	s_add_i32 s21, s18, 1
	s_cmp_lg_u32 s18, 2
	s_cselect_b32 s30, s21, 0
	s_add_i32 s15, s15, 2
	s_add_i32 s76, s76, 64
	s_cmp_eq_u32 s14, s20
	s_cbranch_scc1 .Lmy_exit_dif
	s_mov_b32 s21, s18
	s_mov_b32 s31, s19
	s_mov_b32 s18, s30
	s_mov_b32 s30, s20
	s_add_i32 s20, s30, 1
	s_mov_b32 s19, s21
	s_cmp_ge_i32 s20, s6
	s_waitcnt lgkmcnt(0)
	s_barrier
	s_cbranch_scc0 .LBB0_666
	s_branch .LBB0_669
